# mla_up epilogue start: barrier no longer waits for the next tile's primed LDS-DMA before the per-row SSQ loads are issued
# baseline (speedup 1.0000x reference)
;     ...
;         LAUNDER_TID LANE_DECODE_E(MI)
;         __syncthreads();
;         char* ebuf = smem + (stg ^ 1) * C::STAGE + w * 4608;
;         if (tile < TQ) {
;             const int mt = tile / NTQ, nt = tile % NTQ, tok0 = half * HALF_T + mt * 256;
;             const int wt = nt * C::NWC + wc, head = wt / 3, part = wt - head * 3;
; #pragma unroll
;             for (int mi = 0; mi < MI; ++mi) {
;                 const int tok = tok0 + wr * C::WROWS + mi * 32 + li, tl = tok - half * HALF_T;
;                 const f32x4 s0 = *(const f32x4*)(SSQ + tok * 12), s1 = *(const f32x4*)(SSQ + tok * 12 + 4);
;                 const float rs = __builtin_amdgcn_rsqf(((s0.x + s0.y) + (s0.z + s0.w) + (s1.x + s1.y) + (s1.z + s1.w)) * (1.f / 512.f) + EPS) * QSCALE;
;                 bf16_t* dst = Q + (size_t)tl * 3072 + head * 192 + part * 64;
;                 bf16_t* drow0 = Q + (size_t)(tok0 - half * HALF_T + wr * C::WROWS + mi * 32) * 3072 + head * 192 + part * 64;
;                 if (part < 2) {
;                     wave_rows_store(ebuf, l, drow0, 3072, [&](int ni, int g) { return pk4(acc[mi][ni][4 * g] * rs, acc[mi][ni][4 * g + 1] * rs, acc[mi][ni][4 * g + 2] * rs, acc[mi][ni][4 * g + 3] * rs); });
;                 } else {
; #pragma unroll
;                     for (int g = 0; g < 4; ++g) {
;                         const int i0 = 8 * g + 4 * h;
;                         const f32x4 c4 = *(const f32x4*)(COS + tok * 32 + i0), s4 = *(const f32x4*)(SIN + tok * 32 + i0);
;                         float o1[4], o2[4];
; #pragma unroll
;                         for (int c = 0; c < 4; ++c) { const float x1 = acc[mi][0][4 * g + c] * rs, x2 = acc[mi][1][4 * g + c] * rs; o1[c] = x1 * c4[c] - x2 * s4[c]; o2[c] = x1 * s4[c] + x2 * c4[c]; }
;                         *(u32x2*)(dst + i0) = pk4(o1[0], o1[1], o1[2], o1[3]);
;                         *(u32x2*)(dst + 32 + i0) = pk4(o2[0], o2[1], o2[2], o2[3]);
;                     }
;                 }
;             }
;         } else {
;             const int t2 = tile - TQ, mt = t2 / NTKV, nt = t2 % NTKV, tok0 = half * HALF_T + mt * 256;
;             const int ncol0 = nt * C::BN + wc * 64;
; #pragma unroll
;             for (int mi = 0; mi < MI; ++mi) {
;                 const int tok = tok0 + wr * C::WROWS + mi * 32 + li, tl = tok - half * HALF_T;
;                 const f32x4 s0 = *(const f32x4*)(SSQ + tok * 12 + 8);
.LBB0_801:
	v_mov_b32_e32 v128, v222
	s_xor_b32 s18, s34, 0x10000
	v_ashrrev_i32_e32 v130, 6, v128
	v_lshrrev_b32_e32 v131, 30, v130
	v_add_u32_e32 v131, v130, v131
	v_ashrrev_i32_e32 v243, 2, v131
	v_and_b32_e32 v131, -4, v131
	s_movk_i32 s19, 0x1200
	v_sub_u32_e32 v245, v130, v131
	s_add_i32 s18, s18, 16
	v_mul_lo_u32 v130, v130, s19
	v_and_b32_e32 v129, 63, v128
	v_bfe_u32 v131, v128, 5, 1
	v_and_b32_e32 v244, 31, v128
	v_add_u32_e32 v237, s18, v130
	s_and_b64 vcc, exec, s[4:5]
	s_movk_i32 s4, 0x90
	s_mov_b64 s[18:19], -1
	v_lshlrev_b32_e32 v242, 2, v131
	v_mad_u32_u24 v238, v244, s4, v237
	v_lshrrev_b32_e32 v240, 2, v128
	v_lshrrev_b32_e32 v239, 3, v129
	v_lshlrev_b32_e32 v241, 4, v128
	s_waitcnt lgkmcnt(0)
	s_barrier
	s_cbranch_vccz .LBB0_819
	s_lshl_b32 s4, s44, 4
	s_and_b32 s4, s4, 0x7fffff00
	s_addk_i32 s4, 0xd000
	v_lshl_add_u32 v174, v243, 7, s4
	v_add_u32_e32 v128, s46, v174
	v_or_b32_e32 v246, v244, v128
	v_mul_lo_u32 v204, v246, 12
	v_ashrrev_i32_e32 v205, 31, v204
	v_lshl_add_u64 v[128:129], v[204:205], 2, s[10:11]
	global_load_dwordx4 v[198:201], v[128:129], off offset:32
	s_lshl_b32 s4, s44, 8
	s_and_b32 s4, s4, 0xf00
	v_lshl_add_u32 v196, v245, 6, s4
	s_movk_i32 s4, 0x7ff
	v_cmp_lt_i32_e32 vcc, s4, v196
	v_ashrrev_i32_e32 v128, 1, v174
	s_movk_i32 s4, 0xf800
	v_and_or_b32 v128, v128, s4, v242
	v_add3_u32 v192, v128, v196, s4
	v_or_b32_e32 v194, 1, v192
	v_or_b32_e32 v190, 2, v192
	v_or_b32_e32 v188, 3, v192
	v_or_b32_e32 v186, 8, v192
	v_or_b32_e32 v184, 9, v192
	v_or_b32_e32 v182, 10, v192
	v_or_b32_e32 v180, 11, v192
	v_or_b32_e32 v178, 16, v192
	v_or_b32_e32 v172, 17, v192
	v_or_b32_e32 v170, 18, v192
	v_or_b32_e32 v168, 19, v192
	v_or_b32_e32 v166, 24, v192
	v_or_b32_e32 v164, 25, v192
	v_or_b32_e32 v162, 26, v192
	v_or_b32_e32 v160, 27, v192
	v_or_b32_e32 v158, 32, v192
	v_or_b32_e32 v156, 33, v192
	v_or_b32_e32 v154, 34, v192
	v_or_b32_e32 v152, 35, v192
	v_or_b32_e32 v150, 40, v192
	v_or_b32_e32 v148, 41, v192
	v_or_b32_e32 v146, 42, v192
	v_or_b32_e32 v144, 43, v192
	v_or_b32_e32 v142, 48, v192
	v_or_b32_e32 v140, 49, v192
	v_or_b32_e32 v138, 50, v192
	v_or_b32_e32 v136, 51, v192
	v_or_b32_e32 v134, 56, v192
	v_or_b32_e32 v132, 57, v192
	v_or_b32_e32 v130, 58, v192
	v_or_b32_e32 v128, 59, v192
	v_ashrrev_i32_e32 v193, 31, v192
	v_ashrrev_i32_e32 v195, 31, v194
	v_ashrrev_i32_e32 v191, 31, v190
	v_ashrrev_i32_e32 v189, 31, v188
	v_ashrrev_i32_e32 v187, 31, v186
	v_ashrrev_i32_e32 v185, 31, v184
	v_ashrrev_i32_e32 v183, 31, v182
	v_ashrrev_i32_e32 v181, 31, v180
	v_ashrrev_i32_e32 v179, 31, v178
	v_ashrrev_i32_e32 v173, 31, v172
	v_ashrrev_i32_e32 v171, 31, v170
	v_ashrrev_i32_e32 v169, 31, v168
	v_ashrrev_i32_e32 v167, 31, v166
	v_ashrrev_i32_e32 v165, 31, v164
	v_ashrrev_i32_e32 v163, 31, v162
	v_ashrrev_i32_e32 v161, 31, v160
	v_ashrrev_i32_e32 v159, 31, v158
	v_ashrrev_i32_e32 v157, 31, v156
	v_ashrrev_i32_e32 v155, 31, v154
	v_ashrrev_i32_e32 v153, 31, v152
	v_ashrrev_i32_e32 v151, 31, v150
	v_ashrrev_i32_e32 v149, 31, v148
	v_ashrrev_i32_e32 v147, 31, v146
	v_ashrrev_i32_e32 v145, 31, v144
	v_ashrrev_i32_e32 v143, 31, v142
	v_ashrrev_i32_e32 v141, 31, v140
	v_ashrrev_i32_e32 v139, 31, v138
	v_ashrrev_i32_e32 v137, 31, v136
	v_ashrrev_i32_e32 v135, 31, v134
	v_ashrrev_i32_e32 v133, 31, v132
	s_waitcnt vmcnt(0)
	v_add_f32_e32 v129, v198, v199
	v_add_f32_e32 v131, v200, v201
	v_add_f32_e32 v129, v129, v131
	v_fmamk_f32 v129, v129, 0x3b800000, v252
	v_rsq_f32_e32 v206, v129
	v_ashrrev_i32_e32 v131, 31, v130
	v_ashrrev_i32_e32 v129, 31, v128
	s_and_saveexec_b64 s[4:5], vcc
	s_xor_b64 s[4:5], exec, s[4:5]
	s_cbranch_execz .LBB0_804
; DI bf16_t f2bf(float x) { return (bf16_t)(pk2(x, 0.f) & 0xffffu); }
;     ...
;                     const int bl = tl >> 12, sq = tl & 4095;
; #pragma unroll
;                     for (int ni = 0; ni < 2; ++ni)
; #pragma unroll
;                         for (int r = 0; r < 16; ++r) {
;                             const int n = ncol0 - 2048 + ni * 32 + 8 * (r >> 2) + 4 * h + (r & 3);
;                             VT[((size_t)(bl * 2048 + n)) * 4096 + sq] = f2bf(acc[mi][ni][r] * rs);
;                         }
	v_and_b32_e32 v175, 0xf9f, v246
	v_readlane_b32 s18, v254, 40
	v_lshlrev_b32_e32 v176, 1, v175
	v_readlane_b32 s19, v254, 41
	v_mul_f32_e32 v175, v112, v206
	v_lshlrev_b64 v[200:201], 13, v[192:193]
	v_lshl_add_u64 v[198:199], s[18:19], 0, v[176:177]
	v_cvt_pk_bf16_f32 v175, v175, s0
	v_lshl_add_u64 v[200:201], v[198:199], 0, v[200:201]
	global_store_short v[200:201], v175, off
	v_mul_f32_e32 v175, v113, v206
	v_lshlrev_b64 v[200:201], 13, v[194:195]
	v_cvt_pk_bf16_f32 v175, v175, s0
	v_lshl_add_u64 v[200:201], v[198:199], 0, v[200:201]
	global_store_short v[200:201], v175, off
	v_mul_f32_e32 v175, v114, v206
	v_lshlrev_b64 v[200:201], 13, v[190:191]
	v_cvt_pk_bf16_f32 v175, v175, s0
	v_lshl_add_u64 v[200:201], v[198:199], 0, v[200:201]
	global_store_short v[200:201], v175, off
	v_mul_f32_e32 v175, v115, v206
	v_lshlrev_b64 v[200:201], 13, v[188:189]
	v_cvt_pk_bf16_f32 v175, v175, s0
	v_lshl_add_u64 v[200:201], v[198:199], 0, v[200:201]
	global_store_short v[200:201], v175, off
	v_mul_f32_e32 v175, v116, v206
	v_lshlrev_b64 v[200:201], 13, v[186:187]
	v_cvt_pk_bf16_f32 v175, v175, s0
	v_lshl_add_u64 v[200:201], v[198:199], 0, v[200:201]
	global_store_short v[200:201], v175, off
	v_mul_f32_e32 v175, v117, v206
	v_lshlrev_b64 v[200:201], 13, v[184:185]
	v_cvt_pk_bf16_f32 v175, v175, s0
	v_lshl_add_u64 v[200:201], v[198:199], 0, v[200:201]
	global_store_short v[200:201], v175, off
	v_mul_f32_e32 v175, v118, v206
	v_lshlrev_b64 v[200:201], 13, v[182:183]
	v_cvt_pk_bf16_f32 v175, v175, s0
	v_lshl_add_u64 v[200:201], v[198:199], 0, v[200:201]
	global_store_short v[200:201], v175, off
	v_mul_f32_e32 v175, v119, v206
	v_lshlrev_b64 v[200:201], 13, v[180:181]
	v_cvt_pk_bf16_f32 v175, v175, s0
	v_lshl_add_u64 v[200:201], v[198:199], 0, v[200:201]
	global_store_short v[200:201], v175, off
	v_mul_f32_e32 v175, v120, v206
	v_lshlrev_b64 v[200:201], 13, v[178:179]
	v_cvt_pk_bf16_f32 v175, v175, s0
	v_lshl_add_u64 v[200:201], v[198:199], 0, v[200:201]
	global_store_short v[200:201], v175, off
	v_mul_f32_e32 v175, v121, v206
	v_lshlrev_b64 v[200:201], 13, v[172:173]
	v_cvt_pk_bf16_f32 v175, v175, s0
	v_lshl_add_u64 v[200:201], v[198:199], 0, v[200:201]
	global_store_short v[200:201], v175, off
	v_mul_f32_e32 v175, v122, v206
	v_lshlrev_b64 v[200:201], 13, v[170:171]
	v_cvt_pk_bf16_f32 v175, v175, s0
	v_lshl_add_u64 v[200:201], v[198:199], 0, v[200:201]
	global_store_short v[200:201], v175, off
	v_mul_f32_e32 v175, v123, v206
	v_lshlrev_b64 v[200:201], 13, v[168:169]
	v_cvt_pk_bf16_f32 v175, v175, s0
	v_lshl_add_u64 v[200:201], v[198:199], 0, v[200:201]
	global_store_short v[200:201], v175, off
	v_mul_f32_e32 v175, v124, v206
	v_lshlrev_b64 v[200:201], 13, v[166:167]
	v_cvt_pk_bf16_f32 v175, v175, s0
	v_lshl_add_u64 v[200:201], v[198:199], 0, v[200:201]
	global_store_short v[200:201], v175, off
	v_mul_f32_e32 v175, v125, v206
	v_lshlrev_b64 v[200:201], 13, v[164:165]
	v_cvt_pk_bf16_f32 v175, v175, s0
	v_lshl_add_u64 v[200:201], v[198:199], 0, v[200:201]
	global_store_short v[200:201], v175, off
	v_mul_f32_e32 v175, v126, v206
	v_lshlrev_b64 v[200:201], 13, v[162:163]
	v_cvt_pk_bf16_f32 v175, v175, s0
	v_lshl_add_u64 v[200:201], v[198:199], 0, v[200:201]
	global_store_short v[200:201], v175, off
	v_mul_f32_e32 v175, v127, v206
	v_lshlrev_b64 v[200:201], 13, v[160:161]
	v_cvt_pk_bf16_f32 v175, v175, s0
	v_lshl_add_u64 v[200:201], v[198:199], 0, v[200:201]
	global_store_short v[200:201], v175, off
	v_mul_f32_e32 v175, v96, v206
	v_lshlrev_b64 v[200:201], 13, v[158:159]
	v_cvt_pk_bf16_f32 v175, v175, s0
	v_lshl_add_u64 v[200:201], v[198:199], 0, v[200:201]
	global_store_short v[200:201], v175, off
	v_mul_f32_e32 v175, v97, v206
	v_lshlrev_b64 v[200:201], 13, v[156:157]
	v_cvt_pk_bf16_f32 v175, v175, s0
	v_lshl_add_u64 v[200:201], v[198:199], 0, v[200:201]
	global_store_short v[200:201], v175, off
	v_mul_f32_e32 v175, v98, v206
	v_lshlrev_b64 v[200:201], 13, v[154:155]
	v_cvt_pk_bf16_f32 v175, v175, s0
	v_lshl_add_u64 v[200:201], v[198:199], 0, v[200:201]
	global_store_short v[200:201], v175, off
	v_mul_f32_e32 v175, v99, v206
	v_lshlrev_b64 v[200:201], 13, v[152:153]
	v_cvt_pk_bf16_f32 v175, v175, s0
	v_lshl_add_u64 v[200:201], v[198:199], 0, v[200:201]
	global_store_short v[200:201], v175, off
	v_mul_f32_e32 v175, v100, v206
	v_lshlrev_b64 v[200:201], 13, v[150:151]
	v_cvt_pk_bf16_f32 v175, v175, s0
	v_lshl_add_u64 v[200:201], v[198:199], 0, v[200:201]
	global_store_short v[200:201], v175, off
	v_mul_f32_e32 v175, v101, v206
	v_lshlrev_b64 v[200:201], 13, v[148:149]
	v_cvt_pk_bf16_f32 v175, v175, s0
	v_lshl_add_u64 v[200:201], v[198:199], 0, v[200:201]
	global_store_short v[200:201], v175, off
	v_mul_f32_e32 v175, v102, v206
	v_lshlrev_b64 v[200:201], 13, v[146:147]
	v_cvt_pk_bf16_f32 v175, v175, s0
	v_lshl_add_u64 v[200:201], v[198:199], 0, v[200:201]
	global_store_short v[200:201], v175, off
	v_mul_f32_e32 v175, v103, v206
	v_lshlrev_b64 v[200:201], 13, v[144:145]
	v_cvt_pk_bf16_f32 v175, v175, s0
	v_lshl_add_u64 v[200:201], v[198:199], 0, v[200:201]
	global_store_short v[200:201], v175, off
	v_mul_f32_e32 v175, v104, v206
	v_lshlrev_b64 v[200:201], 13, v[142:143]
	v_cvt_pk_bf16_f32 v175, v175, s0
	v_lshl_add_u64 v[200:201], v[198:199], 0, v[200:201]
	global_store_short v[200:201], v175, off
	v_mul_f32_e32 v175, v105, v206
	v_lshlrev_b64 v[200:201], 13, v[140:141]
	v_cvt_pk_bf16_f32 v175, v175, s0
	v_lshl_add_u64 v[200:201], v[198:199], 0, v[200:201]
	global_store_short v[200:201], v175, off
	v_mul_f32_e32 v175, v106, v206
	v_lshlrev_b64 v[200:201], 13, v[138:139]
	v_cvt_pk_bf16_f32 v175, v175, s0
	v_lshl_add_u64 v[200:201], v[198:199], 0, v[200:201]
	global_store_short v[200:201], v175, off
	v_mul_f32_e32 v175, v107, v206
	v_lshlrev_b64 v[200:201], 13, v[136:137]
	v_cvt_pk_bf16_f32 v175, v175, s0
	v_lshl_add_u64 v[200:201], v[198:199], 0, v[200:201]
	global_store_short v[200:201], v175, off
	v_mul_f32_e32 v175, v108, v206
	v_lshlrev_b64 v[200:201], 13, v[134:135]
	v_cvt_pk_bf16_f32 v175, v175, s0
	v_lshl_add_u64 v[200:201], v[198:199], 0, v[200:201]
	global_store_short v[200:201], v175, off
	v_mul_f32_e32 v175, v109, v206
	v_lshlrev_b64 v[200:201], 13, v[132:133]
	v_cvt_pk_bf16_f32 v175, v175, s0
	v_lshl_add_u64 v[200:201], v[198:199], 0, v[200:201]
	global_store_short v[200:201], v175, off
	v_mul_f32_e32 v175, v110, v206
	v_lshlrev_b64 v[200:201], 13, v[130:131]
	v_cvt_pk_bf16_f32 v175, v175, s0
	v_lshl_add_u64 v[200:201], v[198:199], 0, v[200:201]
	global_store_short v[200:201], v175, off
	v_mul_f32_e32 v175, v111, v206
	v_lshlrev_b64 v[200:201], 13, v[128:129]
	v_cvt_pk_bf16_f32 v175, v175, s0
	v_lshl_add_u64 v[198:199], v[198:199], 0, v[200:201]
	global_store_short v[198:199], v175, off
